# attention steady loop: the step's two LDS-DMA issues moved from the MFMA-free block into phase A's MFMA gaps (slots are free for the whole step)
# speedup vs baseline: 1.0090x; 1.0037x over previous
.LBB0_47:
	v_add_u32_e32 v0, s20, v224
	ds_read_b64_tr_b16 v[2:3], v0 offset:24576
	ds_read_b64_tr_b16 v[4:5], v0 offset:25088
	v_add_f32_e32 v6, v96, v97
	v_add_f32_e32 v6, v98, v6
	v_add_f32_e32 v6, v99, v6
	v_add_f32_e32 v6, v100, v6
	s_waitcnt lgkmcnt(9)
	v_mfma_f32_32x32x16_bf16 v[64:79], v[172:175], v[112:115], v[64:79]
	v_add_f32_e32 v10, v101, v6
	v_cvt_pk_bf16_f32 v140, v96, v97
	v_cvt_pk_bf16_f32 v141, v98, v99
	ds_read_b64_tr_b16 v[6:7], v0 offset:28672
	ds_read_b64_tr_b16 v[8:9], v0 offset:29184
	v_add_f32_e32 v10, v102, v10
	v_add_f32_e32 v10, v103, v10
	v_add_f32_e32 v10, v104, v10
	s_waitcnt lgkmcnt(10)
	v_mfma_f32_32x32x16_bf16 v[48:63], v[168:171], v[112:115], v[48:63]
	v_add_f32_e32 v14, v105, v10
	v_cvt_pk_bf16_f32 v142, v100, v101
	v_cvt_pk_bf16_f32 v143, v102, v103
	s_add_i32 s18, s7, s99
	v_lshl_add_u64 v[250:251], v[194:195], 0, s[24:25]
	s_mov_b32 s20, m0
	s_mov_b32 m0, s18
	s_nop 0
	global_load_lds_dwordx4 v[250:251], off
	s_mov_b32 m0, s20
	ds_read_b64_tr_b16 v[10:11], v0 offset:25600
	ds_read_b64_tr_b16 v[12:13], v0 offset:26112
	v_add_f32_e32 v14, v106, v14
	v_add_f32_e32 v14, v107, v14
	v_add_f32_e32 v14, v108, v14
	s_waitcnt lgkmcnt(11)
	v_mfma_f32_32x32x16_bf16 v[64:79], v[164:167], v[116:119], v[64:79]
	v_add_f32_e32 v14, v109, v14
	v_cvt_pk_bf16_f32 v136, v104, v105
	v_cvt_pk_bf16_f32 v137, v106, v107
	ds_read_b64_tr_b16 v[164:165], v0 offset:29696
	ds_read_b64_tr_b16 v[166:167], v0 offset:30208
	v_add_f32_e32 v14, v110, v14
	v_add_f32_e32 v14, v111, v14
	v_add_f32_e32 v14, v80, v14
	s_waitcnt lgkmcnt(12)
	v_mfma_f32_32x32x16_bf16 v[48:63], v[160:163], v[116:119], v[48:63]
	v_add_f32_e32 v14, v81, v14
	v_cvt_pk_bf16_f32 v138, v108, v109
	v_cvt_pk_bf16_f32 v139, v110, v111
	s_add_i32 s18, s29, s6
	v_lshl_add_u64 v[248:249], v[214:215], 0, s[24:25]
	s_mov_b32 s20, m0
	s_mov_b32 m0, s18
	s_nop 0
	global_load_lds_dwordx4 v[248:249], off
	s_mov_b32 m0, s20
	ds_read_b64_tr_b16 v[168:169], v0 offset:26624
	ds_read_b64_tr_b16 v[170:171], v0 offset:27136
	v_add_f32_e32 v14, v82, v14
	v_add_f32_e32 v14, v83, v14
	v_add_f32_e32 v14, v84, v14
	s_waitcnt lgkmcnt(13)
	v_mfma_f32_32x32x16_bf16 v[64:79], v[156:159], v[120:123], v[64:79]
	v_add_f32_e32 v14, v85, v14
	v_cvt_pk_bf16_f32 v132, v80, v81
	v_cvt_pk_bf16_f32 v133, v82, v83
	ds_read_b64_tr_b16 v[172:173], v0 offset:30720
	ds_read_b64_tr_b16 v[174:175], v0 offset:31232
	v_add_f32_e32 v14, v86, v14
	v_add_f32_e32 v14, v87, v14
	v_add_f32_e32 v14, v88, v14
	s_waitcnt lgkmcnt(14)
	v_mfma_f32_32x32x16_bf16 v[48:63], v[152:155], v[120:123], v[48:63]
	v_add_f32_e32 v14, v89, v14
	v_cvt_pk_bf16_f32 v134, v84, v85
	v_cvt_pk_bf16_f32 v135, v86, v87
	ds_read_b64_tr_b16 v[152:153], v0 offset:27648
	ds_read_b64_tr_b16 v[154:155], v0 offset:28160
	v_add_f32_e32 v14, v90, v14
	v_add_f32_e32 v14, v91, v14
	v_add_f32_e32 v14, v92, v14
	s_waitcnt lgkmcnt(14)
	v_mfma_f32_32x32x16_bf16 v[64:79], v[148:151], v[124:127], v[64:79]
	v_add_f32_e32 v14, v93, v14
	v_cvt_pk_bf16_f32 v128, v88, v89
	v_cvt_pk_bf16_f32 v129, v90, v91
	ds_read_b64_tr_b16 v[184:185], v0 offset:31744
	ds_read_b64_tr_b16 v[186:187], v0 offset:32256
	v_add_f32_e32 v0, v94, v14
	v_add_f32_e32 v0, v95, v0
	v_mfma_f32_32x32x16_bf16 v[48:63], v[144:147], v[124:127], v[48:63]
	v_add_f32_e32 v14, 0, v0
	v_cvt_pk_bf16_f32 v130, v92, v93
	v_cvt_pk_bf16_f32 v131, v94, v95
	v_add_u32_e32 v0, 0, v227
	v_add_u32_e32 v15, 0x15200, v0
	ds_read_b128 v[96:99], v15
	v_add_u32_e32 v15, 0x15280, v0
	ds_read_b128 v[80:83], v15
	v_add_u32_e32 v15, 0x15220, v0
	ds_read_b128 v[100:103], v15
	v_add_u32_e32 v15, 0x152a0, v0
	ds_read_b128 v[84:87], v15
	v_add_u32_e32 v15, 0x15240, v0
	ds_read_b128 v[104:107], v15
	v_add_u32_e32 v15, 0x152c0, v0
	ds_read_b128 v[88:91], v15
	v_add_u32_e32 v15, 0x15260, v0
	ds_read_b128 v[108:111], v15
	v_add_u32_e32 v15, 0x152e0, v0
	ds_read_b128 v[92:95], v15
	s_lshl_b32 s18, 1, s44
	s_and_b32 s18, s18, s81
	s_cmp_lg_u32 s18, 0
	v_add_f32_e32 v14, v225, v14
	s_cselect_b64 s[20:21], -1, 0
	s_cmp_eq_u32 s18, 0
	s_cbranch_scc1 .LBB0_49
	s_add_i32 s18, s33, 0
	s_add_i32 s18, s18, 0x17104
	v_mov_b32_e32 v15, s18
	ds_read_b32 v212, v15
	s_waitcnt lgkmcnt(0)
	v_mul_f32_e32 v14, v14, v212

.LBB0_51:
	s_add_i32 s20, s29, 0x2000
	v_add_u32_e32 v15, s7, v224
	ds_read_b64_tr_b16 v[6:7], v15 offset:24576
	ds_read_b64_tr_b16 v[8:9], v15 offset:25088
	v_add_f32_e32 v128, v64, v65
	v_add_f32_e32 v128, v66, v128
	v_add_f32_e32 v128, v67, v128
	v_add_f32_e32 v128, v68, v128
	s_waitcnt lgkmcnt(9)
	v_mfma_f32_32x32x16_bf16 v[96:111], v[144:147], v[112:115], v[96:111]
	v_add_f32_e32 v128, v69, v128
	v_cvt_pk_bf16_f32 v140, v64, v65
	v_cvt_pk_bf16_f32 v141, v66, v67
	s_cmpk_lg_i32 s29, 0x4000
	s_cselect_b32 s7, s20, 0
	s_add_i32 s18, s29, s99
	ds_read_b64_tr_b16 v[144:145], v15 offset:28672
	ds_read_b64_tr_b16 v[146:147], v15 offset:29184
	v_add_f32_e32 v64, v70, v128
	v_add_f32_e32 v64, v71, v64
	v_add_f32_e32 v64, v72, v64
	s_waitcnt lgkmcnt(10)
	v_mfma_f32_32x32x16_bf16 v[80:95], v[180:183], v[112:115], v[80:95]
	v_add_f32_e32 v64, v73, v64
	v_cvt_pk_bf16_f32 v142, v68, v69
	v_cvt_pk_bf16_f32 v143, v70, v71
	s_mov_b32 s20, m0
	s_mov_b32 m0, s18
	s_nop 0
	global_load_lds_dwordx4 v[194:195], off
	s_mov_b32 m0, s20
	ds_read_b64_tr_b16 v[152:153], v15 offset:25600
	ds_read_b64_tr_b16 v[154:155], v15 offset:26112
	v_add_f32_e32 v64, v74, v64
	v_add_f32_e32 v64, v75, v64
	v_add_f32_e32 v64, v76, v64
	s_waitcnt lgkmcnt(11)
	v_mfma_f32_32x32x16_bf16 v[96:111], v[176:179], v[116:119], v[96:111]
	v_add_f32_e32 v64, v77, v64
	v_cvt_pk_bf16_f32 v136, v72, v73
	v_cvt_pk_bf16_f32 v137, v74, v75
	ds_read_b64_tr_b16 v[176:177], v15 offset:29696
	ds_read_b64_tr_b16 v[178:179], v15 offset:30208
	v_add_f32_e32 v64, v78, v64
	v_add_f32_e32 v64, v79, v64
	v_add_f32_e32 v64, v48, v64
	s_waitcnt lgkmcnt(12)
	v_mfma_f32_32x32x16_bf16 v[80:95], v[160:163], v[116:119], v[80:95]
	v_add_f32_e32 v64, v49, v64
	v_cvt_pk_bf16_f32 v138, v76, v77
	v_cvt_pk_bf16_f32 v139, v78, v79
	s_add_i32 s18, s7, s6
	s_mov_b32 s20, m0
	s_mov_b32 m0, s18
	s_nop 0
	global_load_lds_dwordx4 v[214:215], off
	s_mov_b32 m0, s20
	ds_read_b64_tr_b16 v[180:181], v15 offset:26624
	ds_read_b64_tr_b16 v[182:183], v15 offset:27136
	v_add_f32_e32 v64, v50, v64
	v_add_f32_e32 v64, v51, v64
	v_add_f32_e32 v64, v52, v64
	s_waitcnt lgkmcnt(13)
	v_mfma_f32_32x32x16_bf16 v[96:111], v[156:159], v[120:123], v[96:111]
	v_add_f32_e32 v64, v53, v64
	v_cvt_pk_bf16_f32 v132, v48, v49
	v_cvt_pk_bf16_f32 v133, v50, v51
	ds_read_b64_tr_b16 v[184:185], v15 offset:30720
	ds_read_b64_tr_b16 v[186:187], v15 offset:31232
	v_add_f32_e32 v48, v54, v64
	v_add_f32_e32 v48, v55, v48
	v_add_f32_e32 v48, v56, v48
	s_waitcnt lgkmcnt(14)
	v_mfma_f32_32x32x16_bf16 v[80:95], v[148:151], v[120:123], v[80:95]
	v_add_f32_e32 v48, v57, v48
	v_cvt_pk_bf16_f32 v134, v52, v53
	v_cvt_pk_bf16_f32 v135, v54, v55
	ds_read_b64_tr_b16 v[188:189], v15 offset:27648
	ds_read_b64_tr_b16 v[190:191], v15 offset:28160
	s_waitcnt lgkmcnt(14)
	v_mfma_f32_32x32x16_bf16 v[96:111], v[10:13], v[124:127], v[96:111]
	v_add_f32_e32 v10, v58, v48
	v_add_f32_e32 v10, v59, v10
	v_add_f32_e32 v10, v60, v10
	v_add_f32_e32 v48, v61, v10
	v_cvt_pk_bf16_f32 v128, v56, v57
	v_cvt_pk_bf16_f32 v129, v58, v59
	ds_read_b64_tr_b16 v[10:11], v15 offset:31744
	ds_read_b64_tr_b16 v[12:13], v15 offset:32256
	v_mfma_f32_32x32x16_bf16 v[80:95], v[2:5], v[124:127], v[80:95]
	v_add_f32_e32 v2, v62, v48
	v_add_f32_e32 v2, v63, v2
	v_add_f32_e32 v2, 0, v2
	v_cvt_pk_bf16_f32 v130, v60, v61
	v_cvt_pk_bf16_f32 v131, v62, v63
	v_add_u32_e32 v3, 0x15300, v0
	ds_read_b128 v[64:67], v3
	v_add_u32_e32 v3, 0x15380, v0
	ds_read_b128 v[48:51], v3
	v_add_u32_e32 v3, 0x15320, v0
	ds_read_b128 v[68:71], v3
	v_add_u32_e32 v3, 0x153a0, v0
	ds_read_b128 v[52:55], v3
	v_add_u32_e32 v3, 0x15340, v0
	ds_read_b128 v[72:75], v3
	v_add_u32_e32 v3, 0x153c0, v0
	ds_read_b128 v[56:59], v3
	v_add_u32_e32 v3, 0x15360, v0
	v_add_u32_e32 v0, 0x153e0, v0
	ds_read_b128 v[76:79], v3
	ds_read_b128 v[60:63], v0
	s_lshl_b32 s18, 2, s44
	s_and_b32 s18, s18, s81
	s_cmp_lg_u32 s18, 0
	v_add_f32_e32 v225, v14, v2
	s_cselect_b64 s[20:21], -1, 0
	s_cmp_eq_u32 s18, 0
	s_cbranch_scc1 .LBB0_53
	s_add_i32 s18, s33, 0
	s_add_i32 s18, s18, 0x17108
	v_mov_b32_e32 v0, s18
	ds_read_b32 v212, v0
	s_waitcnt lgkmcnt(0)
	v_mul_f32_e32 v225, v225, v212
